# combined variant plus MLA V-read burst split at the 15-entry lgkmcnt limit (last two reads behind the first bf16 packing)
# speedup vs baseline: 1.0042x; 1.0019x over previous
.LBB0_543:
	ds_read_b128 v[32:35], v105
	ds_read_b128 v[132:135], v105 offset:32
	ds_read_b128 v[48:51], v105 offset:6656
	ds_read_b128 v[136:139], v105 offset:6688
	ds_read_b128 v[140:143], v105 offset:64
	ds_read_b128 v[146:149], v105 offset:96
	ds_read_b128 v[152:155], v105 offset:6720
	ds_read_b128 v[156:159], v105 offset:6752
	ds_read_b128 v[160:163], v105 offset:128
	ds_read_b128 v[164:167], v105 offset:160
	ds_read_b128 v[168:171], v105 offset:6784
	ds_read_b128 v[172:175], v105 offset:6816
	s_waitcnt lgkmcnt(11)
	v_mfma_f32_32x32x16_bf16 v[32:47], v[32:35], v[64:67], 0
	s_waitcnt lgkmcnt(9)
	v_mfma_f32_32x32x16_bf16 v[48:63], v[48:51], v[64:67], 0
	v_mfma_f32_32x32x16_bf16 v[32:47], v[132:135], v[68:71], v[32:47]
	s_waitcnt lgkmcnt(8)
	v_mfma_f32_32x32x16_bf16 v[48:63], v[136:139], v[68:71], v[48:63]
	s_waitcnt lgkmcnt(7)
	v_mfma_f32_32x32x16_bf16 v[32:47], v[140:143], v[72:75], v[32:47]
	s_waitcnt lgkmcnt(5)
	v_mfma_f32_32x32x16_bf16 v[48:63], v[152:155], v[72:75], v[48:63]
	v_mfma_f32_32x32x16_bf16 v[32:47], v[146:149], v[76:79], v[32:47]
	s_waitcnt lgkmcnt(4)
	v_mfma_f32_32x32x16_bf16 v[48:63], v[156:159], v[76:79], v[48:63]
	s_waitcnt lgkmcnt(3)
	v_mfma_f32_32x32x16_bf16 v[32:47], v[160:163], v[80:83], v[32:47]
	s_waitcnt lgkmcnt(1)
	v_mfma_f32_32x32x16_bf16 v[48:63], v[168:171], v[80:83], v[48:63]
	v_mfma_f32_32x32x16_bf16 v[32:47], v[164:167], v[84:87], v[32:47]
	s_waitcnt lgkmcnt(0)
	v_mfma_f32_32x32x16_bf16 v[48:63], v[172:175], v[84:87], v[48:63]
	s_nop 9
	v_exp_f32_e32 v121, v32
	v_exp_f32_e32 v125, v33
	v_exp_f32_e32 v126, v34
	v_exp_f32_e32 v127, v35
	v_exp_f32_e32 v131, v36
	v_exp_f32_e32 v132, v37
	v_exp_f32_e32 v133, v38
	v_exp_f32_e32 v135, v48
	v_exp_f32_e32 v136, v49
	v_exp_f32_e32 v137, v50
	v_exp_f32_e32 v138, v51
	v_exp_f32_e32 v139, v52
	v_exp_f32_e32 v140, v53
	v_exp_f32_e32 v141, v54
	v_exp_f32_e32 v134, v39
	v_exp_f32_e32 v142, v55
	v_exp_f32_e32 v143, v40
	v_exp_f32_e32 v158, v56
	v_exp_f32_e32 v144, v41
	v_exp_f32_e32 v159, v57
	v_exp_f32_e32 v152, v42
	v_exp_f32_e32 v160, v58
	v_exp_f32_e32 v153, v43
	v_exp_f32_e32 v161, v59
	v_exp_f32_e32 v154, v44
	v_exp_f32_e32 v162, v60
	v_exp_f32_e32 v155, v45
	v_exp_f32_e32 v163, v61
	v_exp_f32_e32 v156, v46
	v_exp_f32_e32 v164, v62
	v_exp_f32_e32 v157, v47
	v_exp_f32_e32 v165, v63
	ds_read_b64_tr_b16 v[32:33], v218 offset:13312
	ds_read_b64_tr_b16 v[34:35], v218 offset:14336
	ds_read_b64_tr_b16 v[38:39], v218 offset:14592
	ds_read_b64_tr_b16 v[36:37], v218 offset:13568
	ds_read_b64_tr_b16 v[40:41], v218 offset:15360
	ds_read_b64_tr_b16 v[42:43], v218 offset:16384
	ds_read_b64_tr_b16 v[46:47], v218 offset:16640
	ds_read_b64_tr_b16 v[44:45], v218 offset:15616
	ds_read_b64_tr_b16 v[48:49], v218 offset:17408
	ds_read_b64_tr_b16 v[50:51], v218 offset:18432
	ds_read_b64_tr_b16 v[54:55], v218 offset:18688
	ds_read_b64_tr_b16 v[52:53], v218 offset:17664
	ds_read_b64_tr_b16 v[56:57], v218 offset:19456
	ds_read_b64_tr_b16 v[58:59], v218 offset:20480
	v_cvt_pk_bf16_f32 v146, v121, v125
	v_cvt_pk_bf16_f32 v147, v126, v127
	v_cvt_pk_bf16_f32 v148, v131, v132
	v_cvt_pk_bf16_f32 v149, v133, v134
	ds_read_b64_tr_b16 v[62:63], v218 offset:20736
	ds_read_b64_tr_b16 v[60:61], v218 offset:19712
	s_add_i32 s13, s12, 1
	s_waitcnt lgkmcnt(14)
	v_mfma_f32_32x32x16_bf16 v[16:31], v[32:35], v[146:149], v[16:31]
	v_cvt_pk_bf16_f32 v32, v135, v136
	v_cvt_pk_bf16_f32 v33, v137, v138
	v_cvt_pk_bf16_f32 v34, v139, v140
	v_cvt_pk_bf16_f32 v35, v141, v142
	s_cmp_ge_u32 s13, s31
	s_waitcnt lgkmcnt(12)
	v_mfma_f32_32x32x16_bf16 v[0:15], v[36:39], v[146:149], v[0:15]
	v_cvt_pk_bf16_f32 v36, v143, v144
	v_cvt_pk_bf16_f32 v37, v152, v153
	v_cvt_pk_bf16_f32 v38, v154, v155
	v_cvt_pk_bf16_f32 v39, v156, v157
	s_waitcnt lgkmcnt(10)
	v_mfma_f32_32x32x16_bf16 v[16:31], v[40:43], v[36:39], v[16:31]
	s_waitcnt lgkmcnt(8)
	v_mfma_f32_32x32x16_bf16 v[0:15], v[44:47], v[36:39], v[0:15]
	s_waitcnt lgkmcnt(6)
	v_mfma_f32_32x32x16_bf16 v[16:31], v[48:51], v[32:35], v[16:31]
	s_waitcnt lgkmcnt(4)
	v_mfma_f32_32x32x16_bf16 v[0:15], v[52:55], v[32:35], v[0:15]
	v_cvt_pk_bf16_f32 v32, v158, v159
	v_cvt_pk_bf16_f32 v33, v160, v161
	v_cvt_pk_bf16_f32 v34, v162, v163
	v_cvt_pk_bf16_f32 v35, v164, v165
	s_waitcnt lgkmcnt(2)
	v_mfma_f32_32x32x16_bf16 v[16:31], v[56:59], v[32:35], v[16:31]
	s_waitcnt lgkmcnt(0)
	v_mfma_f32_32x32x16_bf16 v[0:15], v[60:63], v[32:35], v[0:15]
	s_cbranch_scc1 .LBB0_545
	s_cmp_ge_u32 s11, s31
	s_cbranch_scc1 .Lmla_w0_tail
	s_waitcnt vmcnt(5)
	ds_write_b128 v220, v[96:99] offset:21504
	s_waitcnt vmcnt(4)
	ds_write_b128 v219, v[100:103] offset:34816
	s_waitcnt vmcnt(3)
	ds_write_b64 v129, v[114:115] offset:21632
	s_branch .LBB0_545

.LBB0_547:
	ds_read_b128 v[32:35], v105 offset:21504
	ds_read_b128 v[146:149], v105 offset:21536
	ds_read_b128 v[48:51], v105 offset:28160
	ds_read_b128 v[166:169], v105 offset:28192
	ds_read_b128 v[170:173], v105 offset:21568
	ds_read_b128 v[174:177], v105 offset:21600
	ds_read_b128 v[178:181], v105 offset:28224
	ds_read_b128 v[182:185], v105 offset:28256
	ds_read_b128 v[186:189], v105 offset:21632
	ds_read_b128 v[190:193], v105 offset:21664
	ds_read_b128 v[194:197], v105 offset:28288
	ds_read_b128 v[198:201], v105 offset:28320
	s_waitcnt lgkmcnt(11)
	v_mfma_f32_32x32x16_bf16 v[32:47], v[32:35], v[64:67], 0
	v_add_f32_e32 v226, v121, v125
	v_add_f32_e32 v227, v135, v136
	v_add_f32_e32 v226, v126, v226
	s_waitcnt lgkmcnt(9)
	v_mfma_f32_32x32x16_bf16 v[48:63], v[48:51], v[64:67], 0
	v_add_f32_e32 v227, v137, v227
	v_add_f32_e32 v226, v127, v226
	v_add_f32_e32 v227, v138, v227
	v_mfma_f32_32x32x16_bf16 v[32:47], v[146:149], v[68:71], v[32:47]
	v_add_f32_e32 v226, v131, v226
	v_add_f32_e32 v227, v139, v227
	v_add_f32_e32 v226, v132, v226
	s_waitcnt lgkmcnt(8)
	v_mfma_f32_32x32x16_bf16 v[48:63], v[166:169], v[68:71], v[48:63]
	v_add_f32_e32 v227, v140, v227
	v_add_f32_e32 v226, v133, v226
	v_add_f32_e32 v227, v141, v227
	s_waitcnt lgkmcnt(7)
	v_mfma_f32_32x32x16_bf16 v[32:47], v[170:173], v[72:75], v[32:47]
	v_add_f32_e32 v226, v134, v226
	v_add_f32_e32 v227, v142, v227
	v_add_f32_e32 v226, v143, v226
	s_waitcnt lgkmcnt(5)
	v_mfma_f32_32x32x16_bf16 v[48:63], v[178:181], v[72:75], v[48:63]
	v_add_f32_e32 v227, v158, v227
	v_add_f32_e32 v226, v144, v226
	v_add_f32_e32 v227, v159, v227
	v_mfma_f32_32x32x16_bf16 v[32:47], v[174:177], v[76:79], v[32:47]
	v_add_f32_e32 v226, v152, v226
	v_add_f32_e32 v227, v160, v227
	v_add_f32_e32 v226, v153, v226
	s_waitcnt lgkmcnt(4)
	v_mfma_f32_32x32x16_bf16 v[48:63], v[182:185], v[76:79], v[48:63]
	v_add_f32_e32 v227, v161, v227
	v_add_f32_e32 v226, v154, v226
	v_add_f32_e32 v227, v162, v227
	s_waitcnt lgkmcnt(3)
	v_mfma_f32_32x32x16_bf16 v[32:47], v[186:189], v[80:83], v[32:47]
	v_add_f32_e32 v226, v155, v226
	v_add_f32_e32 v227, v163, v227
	v_add_f32_e32 v226, v156, v226
	s_waitcnt lgkmcnt(1)
	v_mfma_f32_32x32x16_bf16 v[48:63], v[194:197], v[80:83], v[48:63]
	v_add_f32_e32 v227, v164, v227
	v_add_f32_e32 v226, v157, v226
	v_add_f32_e32 v227, v165, v227
	v_mfma_f32_32x32x16_bf16 v[32:47], v[190:193], v[84:87], v[32:47]
	v_add_f32_e32 v226, v226, v227
	s_waitcnt lgkmcnt(0)
	v_mfma_f32_32x32x16_bf16 v[48:63], v[198:201], v[84:87], v[48:63]
	s_nop 9
	v_exp_f32_e32 v32, v32
	v_exp_f32_e32 v33, v33
	v_exp_f32_e32 v34, v34
	v_exp_f32_e32 v35, v35
	v_exp_f32_e32 v36, v36
	v_exp_f32_e32 v37, v37
	v_exp_f32_e32 v38, v38
	v_exp_f32_e32 v48, v48
	v_exp_f32_e32 v49, v49
	v_exp_f32_e32 v50, v50
	v_exp_f32_e32 v51, v51
	v_exp_f32_e32 v52, v52
	v_exp_f32_e32 v53, v53
	v_exp_f32_e32 v54, v54
	v_exp_f32_e32 v39, v39
	v_exp_f32_e32 v55, v55
	v_exp_f32_e32 v40, v40
	v_exp_f32_e32 v56, v56
	v_exp_f32_e32 v41, v41
	v_exp_f32_e32 v57, v57
	v_exp_f32_e32 v42, v42
	v_exp_f32_e32 v58, v58
	v_exp_f32_e32 v43, v43
	v_exp_f32_e32 v59, v59
	v_exp_f32_e32 v44, v44
	v_exp_f32_e32 v60, v60
	v_exp_f32_e32 v45, v45
	v_exp_f32_e32 v61, v61
	v_exp_f32_e32 v46, v46
	v_exp_f32_e32 v62, v62
	v_exp_f32_e32 v47, v47
	v_exp_f32_e32 v63, v63
	ds_read_b64_tr_b16 v[146:147], v218 offset:34816
	ds_read_b64_tr_b16 v[148:149], v218 offset:35840
	ds_read_b64_tr_b16 v[168:169], v218 offset:36096
	ds_read_b64_tr_b16 v[166:167], v218 offset:35072
	ds_read_b64_tr_b16 v[170:171], v218 offset:36864
	ds_read_b64_tr_b16 v[172:173], v218 offset:37888
	ds_read_b64_tr_b16 v[176:177], v218 offset:38144
	ds_read_b64_tr_b16 v[174:175], v218 offset:37120
	ds_read_b64_tr_b16 v[178:179], v218 offset:38912
	ds_read_b64_tr_b16 v[180:181], v218 offset:39936
	ds_read_b64_tr_b16 v[184:185], v218 offset:40192
	ds_read_b64_tr_b16 v[182:183], v218 offset:39168
	ds_read_b64_tr_b16 v[186:187], v218 offset:40960
	ds_read_b64_tr_b16 v[188:189], v218 offset:41984
	v_cvt_pk_bf16_f32 v194, v32, v33
	v_cvt_pk_bf16_f32 v195, v34, v35
	v_cvt_pk_bf16_f32 v196, v36, v37
	v_cvt_pk_bf16_f32 v197, v38, v39
	ds_read_b64_tr_b16 v[192:193], v218 offset:42240
	ds_read_b64_tr_b16 v[190:191], v218 offset:41216
	s_andn2_b64 vcc, exec, s[8:9]
	s_waitcnt lgkmcnt(14)
	v_mfma_f32_32x32x16_bf16 v[16:31], v[146:149], v[194:197], v[16:31]
	v_add_f32_e32 v228, v32, v33
	v_add_f32_e32 v229, v48, v49
	v_add_f32_e32 v228, v34, v228
	v_add_f32_e32 v229, v50, v229
	v_cvt_pk_bf16_f32 v146, v48, v49
	v_cvt_pk_bf16_f32 v147, v50, v51
	v_cvt_pk_bf16_f32 v148, v52, v53
	v_cvt_pk_bf16_f32 v149, v54, v55
	s_waitcnt lgkmcnt(12)
	v_mfma_f32_32x32x16_bf16 v[0:15], v[166:169], v[194:197], v[0:15]
	v_add_f32_e32 v228, v35, v228
	v_add_f32_e32 v229, v51, v229
	v_add_f32_e32 v228, v36, v228
	v_add_f32_e32 v229, v52, v229
	v_cvt_pk_bf16_f32 v166, v40, v41
	v_cvt_pk_bf16_f32 v167, v42, v43
	v_cvt_pk_bf16_f32 v168, v44, v45
	v_cvt_pk_bf16_f32 v169, v46, v47
	s_waitcnt lgkmcnt(10)
	v_mfma_f32_32x32x16_bf16 v[16:31], v[170:173], v[166:169], v[16:31]
	v_add_f32_e32 v228, v37, v228
	v_add_f32_e32 v229, v53, v229
	v_add_f32_e32 v228, v38, v228
	v_add_f32_e32 v229, v54, v229
	s_waitcnt lgkmcnt(8)
	v_mfma_f32_32x32x16_bf16 v[0:15], v[174:177], v[166:169], v[0:15]
	v_add_f32_e32 v228, v39, v228
	v_add_f32_e32 v229, v55, v229
	v_add_f32_e32 v228, v40, v228
	v_add_f32_e32 v229, v56, v229
	s_waitcnt lgkmcnt(6)
	v_mfma_f32_32x32x16_bf16 v[16:31], v[178:181], v[146:149], v[16:31]
	v_add_f32_e32 v228, v41, v228
	v_add_f32_e32 v229, v57, v229
	v_add_f32_e32 v228, v42, v228
	v_add_f32_e32 v229, v58, v229
	s_waitcnt lgkmcnt(4)
	v_mfma_f32_32x32x16_bf16 v[0:15], v[182:185], v[146:149], v[0:15]
	v_add_f32_e32 v228, v43, v228
	v_add_f32_e32 v229, v59, v229
	v_add_f32_e32 v228, v44, v228
	v_add_f32_e32 v229, v60, v229
	v_cvt_pk_bf16_f32 v146, v56, v57
	v_cvt_pk_bf16_f32 v147, v58, v59
	v_cvt_pk_bf16_f32 v148, v60, v61
	v_cvt_pk_bf16_f32 v149, v62, v63
	s_waitcnt lgkmcnt(2)
	v_mfma_f32_32x32x16_bf16 v[16:31], v[186:189], v[146:149], v[16:31]
	v_add_f32_e32 v228, v45, v228
	v_add_f32_e32 v229, v61, v229
	v_add_f32_e32 v228, v46, v228
	v_add_f32_e32 v229, v62, v229
	s_waitcnt lgkmcnt(0)
	v_mfma_f32_32x32x16_bf16 v[0:15], v[190:193], v[146:149], v[0:15]
	v_add_f32_e32 v228, v47, v228
	v_add_f32_e32 v229, v63, v229
	v_add_f32_e32 v228, v228, v229
	s_cbranch_vccnz .LBB0_549
	s_add_i32 s13, s10, 2
	s_cmp_ge_u32 s11, s13
	s_cbranch_scc1 .Lmla_w1_tail
	s_waitcnt vmcnt(5)
	ds_write_b128 v220, v[88:91]
	s_waitcnt vmcnt(4)
	ds_write_b128 v219, v[92:95] offset:13312
	s_waitcnt vmcnt(3)
	ds_write_b64 v129, v[116:117] offset:128
	s_branch .LBB0_549
